# kept version plus nt hint on prompt-attention OPART/LPART partial stores and on the GLA prompt read-once loads, to leave Q/K/V resident for the second and third branch sweeps
# baseline (speedup 1.0000x reference)
; #define LAS __attribute__((address_space(3)))
; #define LBAR() do { asm volatile("s_waitcnt lgkmcnt(0)" ::: "memory"); __builtin_amdgcn_s_barrier(); asm volatile("" ::: "memory"); } while (0)
; __device__ __forceinline__ unsigned pk2(float lo, float hi) { typedef float f2 __attribute__((ext_vector_type(2))); typedef __bf16 b2 __attribute__((ext_vector_type(2))); f2 v = {lo, hi}; b2 b = __builtin_convertvector(v, b2); return __builtin_bit_cast(unsigned, b); }
; __device__ __forceinline__ float fast_exp(float x) { return __builtin_amdgcn_exp2f(x * LOG2E); }
; __device__ __forceinline__ void gla_prompt_item(Frame& F, int b, int h) {
;     ...
;         f32x2 cs[4]; cs[0] = lg[0];
; #pragma unroll
;         for (int i = 1; i < 4; ++i) cs[i] = cs[i - 1] + lg[i];
;         *(LAS f32x2*)(L + G_TOT + (seg * 64 + 2 * kp) * 4) = cs[3];
; #pragma unroll
;         for (int i = 0; i < 2; ++i) { const int p_ = tid + 512 * i, row_ = p_ >> 4, c_ = p_ & 15; *(LAS v4u*)(L + G_V + row_ * G_VP + c_ * 16) = vv[i]; }
;         LBAR();
;         if (n > 0) {
; #pragma unroll
;             for (int i = 0; i < 2; ++i) *(v4u*)(MIX + (t0 - 64 + et) * DM + DA + h * 128 + 16 * evc + 8 * i) = outp[i];
;         }
;         f32x2 pre = {0.f, 0.f}, tot = {0.f, 0.f};
; #pragma unroll
;         for (int s = 0; s < 16; ++s) { const f32x2 v = *(const LAS f32x2*)(L + G_TOT + (s * 64 + 2 * kp) * 4); if (s < seg) pre += v; tot += v; }
; #pragma unroll
;         for (int i = 0; i < 4; ++i) {
;             f32x2 bb = pre + cs[i]; bb.x = fmaxf(bb.x, -80.f); bb.y = fmaxf(bb.y, -80.f);
;             const float ep0 = fast_exp(bb.x), ep1 = fast_exp(bb.y), em0 = fast_exp(-bb.x), em1 = fast_exp(-bb.y);
;             const int t = 4 * seg + i;
;             *(LAS unsigned*)(L + G_QT + t * G_RP + kp * 4) = pk2(bflo(qv[i]) * ep0, bfhi(qv[i]) * ep1);
;             *(LAS unsigned*)(L + G_KT + t * G_RP + kp * 4) = pk2(bflo(kv[i]) * em0, bfhi(kv[i]) * em1);
;         }
;         if (seg == 0) { f32x2 dd; dd.x = fast_exp(fmaxf(tot.x, -80.f)); dd.y = fast_exp(fmaxf(tot.y, -80.f)); *(LAS f32x2*)(L + G_D + 2 * kp * 4) = dd; }
; #pragma unroll
;         for (int i = 0; i < 2; ++i) gg[i] = *(const v4u*)(GBp + (t0 + et) * 512 + h * 128 + 16 * evc + 8 * i);
;         if (n + 1 < SEQ / 64 && var != 2) GLA_LOAD(n + 1);
.LBB0_595:
	v_pk_add_f32 v[140:141], v[80:81], v[78:79]
	v_add_u32_e32 v42, 0, v1
	v_pk_add_f32 v[142:143], v[140:141], v[82:83]
	v_add_u32_e32 v66, 0x13800, v42
	v_pk_add_f32 v[144:145], v[142:143], v[84:85]
	ds_write_b64 v99, v[144:145]
	ds_write_b128 v96, v[18:21] offset:18432
	ds_write_b128 v97, v[22:25] offset:18432
	s_waitcnt lgkmcnt(0)
	s_barrier
	v_lshl_add_u64 v[54:55], s[58:59], 0, v[94:95]
	ds_read2_b64 v[42:45], v66 offset1:32
	v_add_co_u32_e32 v54, vcc, s33, v54
	v_add_u32_e32 v139, 0x800, v66
	s_nop 0
	v_addc_co_u32_e32 v55, vcc, 0, v55, vcc
	global_store_dwordx4 v[54:55], v[50:53], off offset:1024
	global_store_dwordx4 v[54:55], v[46:49], off offset:1040
	v_lshl_add_u64 v[212:213], s[58:59], 0, v[92:93]
	v_lshl_add_u64 v[214:215], v[212:213], 0, s[74:75]
	v_add_co_u32_e32 v212, vcc, 0x27c10000, v212
	s_nop 1
	v_addc_co_u32_e32 v213, vcc, 0, v213, vcc
	global_load_dwordx4 v[220:223], v[212:213], off nt
	global_load_dwordx4 v[224:227], v[214:215], off offset:16 nt
	s_cmp_eq_u32 s1, 1
	s_cbranch_scc1 .Lgla_nopf
	v_lshl_add_u64 v[212:213], s[58:59], 0, v[90:91]
	v_add_co_u32_e32 v214, vcc, 0x1f410000, v212
	s_nop 1
	v_addc_co_u32_e32 v215, vcc, 0, v213, vcc
	v_add_co_u32_e32 v216, vcc, 0x16c10000, v212
	s_nop 1
	v_addc_co_u32_e32 v217, vcc, 0, v213, vcc
	v_add_co_u32_e32 v218, vcc, 0x18e10000, v212
	s_nop 1
	v_addc_co_u32_e32 v219, vcc, 0, v213, vcc
	global_load_dword v192, v[214:215], off nt
	global_load_dword v196, v[216:217], off nt
	global_load_dword v193, v[214:215], off offset:512 nt
	global_load_dword v197, v[216:217], off offset:512 nt
	global_load_dword v194, v[214:215], off offset:1024 nt
	global_load_dword v198, v[216:217], off offset:1024 nt
	global_load_dword v199, v[216:217], off offset:1536 nt
	global_load_dword v195, v[214:215], off offset:1536 nt
	v_lshl_add_u64 v[212:213], s[58:59], 0, v[88:89]
	v_lshl_add_u64 v[214:215], s[58:59], 0, v[86:87]
	global_load_dwordx4 v[200:203], v[212:213], off nt
	global_load_dwordx4 v[204:207], v[214:215], off nt
	global_load_dword v208, v[218:219], off nt
	global_load_dword v209, v[218:219], off offset:512 nt
	global_load_dword v210, v[218:219], off offset:1024 nt
	global_load_dword v211, v[218:219], off offset:1536 nt

; __device__ __forceinline__ int attn_prompt_loop(Frame& F, int t) {
;     ...
;         const bool h1 = have_st;
;         if (have_st) {
;             *(v4u*)(ostp) = ost[0]; *(v4u*)(ostp + 32) = ost[1];
;             if (g4 == 0) *lstp = lst;
;             have_st = false;
.LBB0_670:
	s_waitcnt lgkmcnt(0)
	s_barrier
	s_andn2_b64 vcc, exec, s[64:65]
	s_cbranch_vccnz .LBB0_674
	s_waitcnt lgkmcnt(1)
	global_store_dwordx4 v[126:127], v[6:9], off nt
	s_waitcnt lgkmcnt(0)
	global_store_dwordx4 v[126:127], v[10:13], off offset:64 nt
	s_mov_b64 s[26:27], exec
	v_readlane_b32 s34, v246, 53
	v_readlane_b32 s35, v246, 54
	s_and_b64 s[34:35], s[26:27], s[34:35]
	s_mov_b64 exec, s[34:35]
	s_cbranch_execz .LBB0_673
	global_store_dword v[124:125], v123, off nt

; __device__ __forceinline__ int attn_prompt_loop(Frame& F, int t) {
;     ...
;     if (have_st) {
;         *(v4u*)(ostp) = ost[0]; *(v4u*)(ostp + 32) = ost[1];
;         if (g4 == 0) *lstp = lst;
;     }
.LBB0_769:
	v_readlane_b32 s96, v246, 8
	v_readlane_b32 s90, v246, 2
	s_andn2_b64 vcc, exec, s[26:27]
	v_readlane_b32 s97, v246, 9
	v_readlane_b32 s86, v246, 5
	v_readlane_b32 s88, v246, 4
	v_readlane_b32 s91, v246, 3
	s_cbranch_vccnz .LBB0_773
	s_waitcnt lgkmcnt(1)
	global_store_dwordx4 v[126:127], v[6:9], off nt
	s_waitcnt lgkmcnt(0)
	global_store_dwordx4 v[126:127], v[10:13], off offset:64 nt
	s_mov_b64 s[4:5], exec
	v_readlane_b32 s0, v246, 53
	v_readlane_b32 s1, v246, 54
	s_and_b64 s[0:1], s[4:5], s[0:1]
	s_mov_b64 exec, s[0:1]
	s_cbranch_execz .LBB0_772
	global_store_dword v[124:125], v123, off nt

; __device__ __forceinline__ int attn_prompt_loop(Frame& F, int t) {
;     ...
;         const bool h1 = have_st;
;         if (have_st) {
;             *(v4u*)(ostp) = ost[0]; *(v4u*)(ostp + 32) = ost[1];
;             if (g4 == 0) *lstp = lst;
;             have_st = false;
.LBB0_999:
	s_waitcnt lgkmcnt(0)
	s_barrier
	s_andn2_b64 vcc, exec, s[66:67]
	s_cbranch_vccnz .LBB0_1003
	s_waitcnt lgkmcnt(1)
	global_store_dwordx4 v[126:127], v[6:9], off nt
	s_waitcnt lgkmcnt(0)
	global_store_dwordx4 v[126:127], v[10:13], off offset:64 nt
	s_mov_b64 s[26:27], exec
	v_readlane_b32 s30, v246, 13
	v_readlane_b32 s31, v246, 14
	s_and_b64 s[30:31], s[26:27], s[30:31]
	s_mov_b64 exec, s[30:31]
	s_cbranch_execz .LBB0_1002
	global_store_dword v[124:125], v123, off nt

; __device__ __forceinline__ int attn_prompt_loop(Frame& F, int t) {
;     ...
;     if (have_st) {
;         *(v4u*)(ostp) = ost[0]; *(v4u*)(ostp + 32) = ost[1];
;         if (g4 == 0) *lstp = lst;
;     }
.LBB0_1097:
	v_readlane_b32 s96, v246, 8
	v_readlane_b32 s90, v246, 2
	s_andn2_b64 vcc, exec, s[26:27]
	v_readlane_b32 s97, v246, 9
	v_readlane_b32 s86, v246, 5
	v_readlane_b32 s88, v246, 4
	v_readlane_b32 s91, v246, 3
	s_cbranch_vccnz .LBB0_1101
	s_waitcnt lgkmcnt(1)
	global_store_dwordx4 v[126:127], v[6:9], off nt
	s_waitcnt lgkmcnt(0)
	global_store_dwordx4 v[126:127], v[10:13], off offset:64 nt
	s_mov_b64 s[4:5], exec
	v_readlane_b32 s0, v246, 13
	v_readlane_b32 s1, v246, 14
	s_and_b64 s[0:1], s[4:5], s[0:1]
	s_mov_b64 exec, s[0:1]
	s_cbranch_execz .LBB0_1100
	global_store_dword v[124:125], v123, off nt
